# v74 plus F-phase sample-row chunk loads batched (14 loads hoisted, copied at the original sites)
# speedup vs baseline: 1.0161x; 1.0036x over previous
.LBB0_1222:
	s_abs_i32 s10, s8
	v_readlane_b32 s11, v253, 56
	s_mul_hi_u32 s11, s10, s11
	v_readlane_b32 s18, v253, 57
	s_mul_i32 s16, s11, s18
	s_ashr_i32 s9, s8, 31
	s_sub_i32 s10, s10, s16
	s_xor_b32 s9, s9, s43
	s_add_i32 s16, s11, 1
	s_sub_i32 s17, s10, s18
	s_cmp_ge_u32 s10, s18
	s_cselect_b32 s11, s16, s11
	s_cselect_b32 s10, s17, s10
	s_add_i32 s16, s11, 1
	s_cmp_ge_u32 s10, s18
	s_cselect_b32 s10, s16, s11
	s_xor_b32 s10, s10, s9
	s_sub_i32 s9, s10, s9
	s_add_i32 s9, s8, s9
	s_and_b32 s9, s9, 7
	v_readlane_b32 s10, v253, 15
	s_cmp_lg_u32 s10, s9
	s_cbranch_scc1 .LBB0_1221
	s_lshr_b32 s9, s8, 3
	s_add_i32 s16, s8, 0x2000
	s_add_i32 s9, s9, 1
	s_cmp_gt_i32 s8, -1
	s_cselect_b32 s9, s9, 0
	s_add_i32 s9, s9, s97
	s_mul_hi_u32 s11, s9, 0xc000
	s_mul_i32 s9, s9, 0xc000
	s_add_u32 s10, s26, s9
	v_lshl_add_u64 v[2:3], s[14:15], 0, v[12:13]
	s_mov_b32 s9, 0x3af5e000
	v_add_co_u32_e32 v8, vcc, s9, v2
	s_mov_b32 s9, 0x3af5f000
	s_nop 0
	v_addc_co_u32_e32 v9, vcc, 0, v3, vcc
	v_add_co_u32_e32 v62, vcc, s9, v2
	s_mov_b32 s9, 0x3b15e000
	s_nop 0
	v_addc_co_u32_e32 v63, vcc, 0, v3, vcc
	global_load_dwordx4 v[4:7], v[62:63], off offset:-4096
	global_load_dwordx4 v[38:41], v[8:9], off offset:1024
	global_load_dwordx4 v[42:45], v[8:9], off offset:2048
	global_load_dwordx4 v[46:49], v[8:9], off offset:3072
	global_load_dwordx4 v[50:53], v[62:63], off
	global_load_dwordx4 v[54:57], v[62:63], off offset:1024
	global_load_dwordx4 v[58:61], v[62:63], off offset:2048
	s_nop 0
	global_load_dwordx4 v[62:65], v[62:63], off offset:3072
	v_add_co_u32_e32 v8, vcc, s9, v2
	s_mov_b32 s9, 0x3b15f000
	s_nop 0
	v_addc_co_u32_e32 v9, vcc, 0, v3, vcc
	v_add_co_u32_e32 v96, vcc, s9, v2
	s_mov_b32 s9, 0x3b35e000
	s_nop 0
	v_addc_co_u32_e32 v97, vcc, 0, v3, vcc
	global_load_dwordx4 v[66:69], v[96:97], off offset:-4096
	global_load_dwordx4 v[70:73], v[8:9], off offset:1024
	global_load_dwordx4 v[74:77], v[8:9], off offset:2048
	global_load_dwordx4 v[78:81], v[8:9], off offset:3072
	global_load_dwordx4 v[84:87], v[96:97], off
	global_load_dwordx4 v[88:91], v[96:97], off offset:1024
	global_load_dwordx4 v[92:95], v[96:97], off offset:2048
	s_nop 0
	global_load_dwordx4 v[96:99], v[96:97], off offset:3072
	v_add_co_u32_e32 v8, vcc, s9, v2
	s_mov_b32 s9, 0x3b35f000
	s_nop 0
	v_addc_co_u32_e32 v9, vcc, 0, v3, vcc
	v_add_co_u32_e32 v128, vcc, s9, v2
	s_mov_b32 s9, 0x3b55e000
	s_nop 0
	v_addc_co_u32_e32 v129, vcc, 0, v3, vcc
	global_load_dwordx4 v[100:103], v[128:129], off offset:-4096
	global_load_dwordx4 v[104:107], v[8:9], off offset:1024
	global_load_dwordx4 v[108:111], v[8:9], off offset:2048
	global_load_dwordx4 v[112:115], v[8:9], off offset:3072
	global_load_dwordx4 v[116:119], v[128:129], off
	global_load_dwordx4 v[120:123], v[128:129], off offset:1024
	global_load_dwordx4 v[124:127], v[128:129], off offset:2048
	s_nop 0
	global_load_dwordx4 v[128:131], v[128:129], off offset:3072
	s_addc_u32 s11, s27, s11
	s_ashr_i32 s17, s16, 31
	s_waitcnt vmcnt(15)
	v_pk_add_f32 v[6:7], v[6:7], v[68:69]
	s_waitcnt vmcnt(14)
	v_pk_add_f32 v[8:9], v[40:41], v[72:73]
	s_waitcnt vmcnt(13)
	v_pk_add_f32 v[42:43], v[42:43], v[74:75]
	v_pk_add_f32 v[40:41], v[44:45], v[76:77]
	s_waitcnt vmcnt(12)
	v_pk_add_f32 v[44:45], v[48:49], v[80:81]
	s_waitcnt vmcnt(11)
	v_pk_add_f32 v[48:49], v[52:53], v[86:87]
	s_waitcnt vmcnt(10)
	v_pk_add_f32 v[52:53], v[56:57], v[90:91]
	s_waitcnt vmcnt(9)
	v_pk_add_f32 v[56:57], v[60:61], v[94:95]
	s_waitcnt vmcnt(8)
	v_pk_add_f32 v[60:61], v[64:65], v[98:99]
	v_pk_add_f32 v[58:59], v[58:59], v[92:93]
	v_pk_add_f32 v[4:5], v[4:5], v[66:67]
	v_pk_add_f32 v[38:39], v[38:39], v[70:71]
	v_pk_add_f32 v[50:51], v[50:51], v[84:85]
	s_waitcnt vmcnt(5)
	v_pk_add_f32 v[74:75], v[42:43], v[108:109]
	v_add_co_u32_e32 v42, vcc, s9, v2
	s_mov_b32 s9, 0x3b55f000
	s_nop 0
	v_addc_co_u32_e32 v43, vcc, 0, v3, vcc
	s_waitcnt vmcnt(0)
	v_pk_add_f32 v[92:93], v[60:61], v[130:131]
	v_add_co_u32_e32 v60, vcc, s9, v2
	v_pk_add_f32 v[54:55], v[54:55], v[88:89]
	v_pk_add_f32 v[62:63], v[62:63], v[96:97]
	v_addc_co_u32_e32 v61, vcc, 0, v3, vcc
	v_pk_add_f32 v[46:47], v[46:47], v[78:79]
	v_pk_add_f32 v[64:65], v[6:7], v[102:103]
	v_pk_add_f32 v[66:67], v[4:5], v[100:101]
	v_pk_add_f32 v[68:69], v[8:9], v[106:107]
	v_pk_add_f32 v[70:71], v[38:39], v[104:105]
	v_pk_add_f32 v[72:73], v[40:41], v[110:111]
	v_pk_add_f32 v[76:77], v[44:45], v[114:115]
	v_pk_add_f32 v[78:79], v[48:49], v[118:119]
	v_pk_add_f32 v[80:81], v[50:51], v[116:117]
	v_pk_add_f32 v[84:85], v[52:53], v[122:123]
	v_pk_add_f32 v[86:87], v[54:55], v[120:121]
	v_pk_add_f32 v[88:89], v[56:57], v[126:127]
	v_pk_add_f32 v[90:91], v[58:59], v[124:125]
	v_pk_add_f32 v[94:95], v[62:63], v[128:129]
	global_load_dwordx4 v[2:5], v[60:61], off offset:-4096
	global_load_dwordx4 v[6:9], v[42:43], off offset:1024
	global_load_dwordx4 v[38:41], v[42:43], off offset:2048
	s_nop 0
	global_load_dwordx4 v[42:45], v[42:43], off offset:3072
	s_nop 0
	global_load_dwordx4 v[48:51], v[60:61], off
	global_load_dwordx4 v[52:55], v[60:61], off offset:1024
	global_load_dwordx4 v[56:59], v[60:61], off offset:2048
	s_nop 0
	global_load_dwordx4 v[60:63], v[60:61], off offset:3072
	s_movk_i32 s9, 0x5000
	v_pk_add_f32 v[46:47], v[46:47], v[112:113]
	s_waitcnt vmcnt(7)
	v_pk_add_f32 v[64:65], v[4:5], v[64:65]
	s_waitcnt vmcnt(6)
	v_pk_add_f32 v[96:97], v[8:9], v[68:69]
	v_pk_add_f32 v[98:99], v[6:7], v[70:71]
	v_pk_add_f32 v[66:67], v[2:3], v[66:67]
	s_waitcnt vmcnt(4)
	v_pk_add_f32 v[44:45], v[44:45], v[76:77]
	s_waitcnt vmcnt(2)
	v_pk_add_f32 v[8:9], v[54:55], v[84:85]
	v_lshl_add_u64 v[54:55], v[10:11], 2, s[10:11]
	v_add_co_u32_e32 v6, vcc, s9, v54
	s_waitcnt vmcnt(1)
	v_pk_add_f32 v[2:3], v[58:59], v[88:89]
	v_addc_co_u32_e32 v7, vcc, 0, v55, vcc
	v_pk_add_f32 v[4:5], v[56:57], v[90:91]
	global_load_dwordx4 v[56:59], v[6:7], off offset:-4096
	v_lshl_add_u64 v[76:77], s[12:13], 0, v[12:13]
	v_pk_add_f32 v[72:73], v[40:41], v[72:73]
	v_pk_add_f32 v[46:47], v[42:43], v[46:47]
	v_pk_add_f32 v[40:41], v[50:51], v[78:79]
	v_pk_add_f32 v[42:43], v[48:49], v[80:81]
	global_load_dwordx4 v[48:51], v[76:77], off
	v_mov_b32_e32 v146, 0x1000
	v_mov_b32_e32 v147, 0
	v_lshl_add_u64 v[144:145], v[76:77], 0, v[146:147]
	global_load_dwordx4 v[180:183], v[76:77], off offset:1024
	global_load_dwordx4 v[184:187], v[6:7], off offset:-3072
	global_load_dwordx4 v[188:191], v[76:77], off offset:2048
	global_load_dwordx4 v[192:195], v[6:7], off offset:-2048
	global_load_dwordx4 v[196:199], v[76:77], off offset:3072
	global_load_dwordx4 v[200:203], v[6:7], off offset:-1024
	global_load_dwordx4 v[204:207], v[144:145], off
	global_load_dwordx4 v[208:211], v[6:7], off
	global_load_dwordx4 v[212:215], v[144:145], off offset:1024
	global_load_dwordx4 v[216:219], v[6:7], off offset:1024
	global_load_dwordx4 v[220:223], v[144:145], off offset:2048
	global_load_dwordx4 v[236:239], v[6:7], off offset:2048
	global_load_dwordx4 v[240:243], v[144:145], off offset:3072
	global_load_dwordx4 v[140:143], v[6:7], off offset:3072
	s_mov_b64 s[10:11], 0x4000
	v_pk_add_f32 v[74:75], v[38:39], v[74:75]
	v_pk_add_f32 v[38:39], v[52:53], v[86:87]
	v_lshl_add_u64 v[52:53], v[54:55], 0, s[10:11]
	s_waitcnt vmcnt(2)
	v_pk_add_f32 v[68:69], v[62:63], v[92:93]
	v_pk_add_f32 v[70:71], v[60:61], v[94:95]
	s_mov_b32 s9, 0x9000
	s_waitcnt vmcnt(1)
	v_pk_add_f32 v[58:59], v[58:59], 1.0 op_sel_hi:[1,0]
	v_pk_add_f32 v[56:57], v[56:57], 1.0 op_sel_hi:[1,0]
	v_pk_mul_f32 v[58:59], v[58:59], v[64:65]
	v_pk_mul_f32 v[56:57], v[56:57], v[66:67]
	s_waitcnt vmcnt(0)
	v_pk_fma_f32 v[64:65], v[50:51], s[92:93], v[58:59] op_sel_hi:[1,0,1]
	v_pk_fma_f32 v[66:67], v[48:49], s[92:93], v[56:57] op_sel_hi:[1,0,1]
	v_mov_b64_e32 v[48:49], v[180:181]
	v_mov_b64_e32 v[50:51], v[182:183]
	v_mov_b64_e32 v[56:57], v[184:185]
	v_mov_b64_e32 v[58:59], v[186:187]
	s_waitcnt vmcnt(0)
	v_pk_add_f32 v[58:59], v[58:59], 1.0 op_sel_hi:[1,0]
	v_pk_add_f32 v[56:57], v[56:57], 1.0 op_sel_hi:[1,0]
	v_pk_mul_f32 v[58:59], v[96:97], v[58:59]
	v_pk_mul_f32 v[56:57], v[98:99], v[56:57]
	v_pk_fma_f32 v[60:61], v[50:51], s[92:93], v[58:59] op_sel_hi:[1,0,1]
	v_pk_fma_f32 v[62:63], v[48:49], s[92:93], v[56:57] op_sel_hi:[1,0,1]
	v_mov_b64_e32 v[48:49], v[188:189]
	v_mov_b64_e32 v[50:51], v[190:191]
	v_mov_b64_e32 v[56:57], v[192:193]
	v_mov_b64_e32 v[58:59], v[194:195]
	s_waitcnt vmcnt(0)
	v_pk_add_f32 v[58:59], v[58:59], 1.0 op_sel_hi:[1,0]
	v_pk_add_f32 v[56:57], v[56:57], 1.0 op_sel_hi:[1,0]
	v_pk_mul_f32 v[58:59], v[58:59], v[72:73]
	v_pk_mul_f32 v[56:57], v[56:57], v[74:75]
	v_pk_fma_f32 v[58:59], v[50:51], s[92:93], v[58:59] op_sel_hi:[1,0,1]
	v_pk_fma_f32 v[56:57], v[48:49], s[92:93], v[56:57] op_sel_hi:[1,0,1]
	v_mov_b64_e32 v[48:49], v[196:197]
	v_mov_b64_e32 v[50:51], v[198:199]
	v_mov_b64_e32 v[72:73], v[200:201]
	v_mov_b64_e32 v[74:75], v[202:203]
	v_add_co_u32_e32 v76, vcc, s82, v76
	s_waitcnt vmcnt(0)
	v_pk_add_f32 v[52:53], v[74:75], 1.0 op_sel_hi:[1,0]
	v_pk_add_f32 v[72:73], v[72:73], 1.0 op_sel_hi:[1,0]
	v_pk_mul_f32 v[44:45], v[44:45], v[52:53]
	v_pk_mul_f32 v[46:47], v[46:47], v[72:73]
	v_addc_co_u32_e32 v77, vcc, 0, v77, vcc
	v_pk_fma_f32 v[52:53], v[50:51], s[92:93], v[44:45] op_sel_hi:[1,0,1]
	v_pk_fma_f32 v[50:51], v[48:49], s[92:93], v[46:47] op_sel_hi:[1,0,1]
	v_mov_b64_e32 v[44:45], v[204:205]
	v_mov_b64_e32 v[46:47], v[206:207]
	v_mov_b64_e32 v[72:73], v[208:209]
	v_mov_b64_e32 v[74:75], v[210:211]
	s_waitcnt vmcnt(0)
	v_pk_add_f32 v[48:49], v[74:75], 1.0 op_sel_hi:[1,0]
	v_pk_add_f32 v[72:73], v[72:73], 1.0 op_sel_hi:[1,0]
	v_pk_mul_f32 v[40:41], v[48:49], v[40:41]
	v_pk_mul_f32 v[42:43], v[72:73], v[42:43]
	v_pk_fma_f32 v[48:49], v[46:47], s[92:93], v[40:41] op_sel_hi:[1,0,1]
	v_pk_fma_f32 v[46:47], v[44:45], s[92:93], v[42:43] op_sel_hi:[1,0,1]
	v_mov_b64_e32 v[40:41], v[212:213]
	v_mov_b64_e32 v[42:43], v[214:215]
	v_mov_b64_e32 v[72:73], v[216:217]
	v_mov_b64_e32 v[74:75], v[218:219]
	s_waitcnt vmcnt(0)
	v_pk_add_f32 v[44:45], v[74:75], 1.0 op_sel_hi:[1,0]
	v_pk_add_f32 v[72:73], v[72:73], 1.0 op_sel_hi:[1,0]
	v_pk_mul_f32 v[8:9], v[8:9], v[44:45]
	v_pk_mul_f32 v[38:39], v[38:39], v[72:73]
	v_pk_fma_f32 v[44:45], v[42:43], s[92:93], v[8:9] op_sel_hi:[1,0,1]
	v_pk_fma_f32 v[42:43], v[40:41], s[92:93], v[38:39] op_sel_hi:[1,0,1]
	v_mov_b64_e32 v[38:39], v[220:221]
	v_mov_b64_e32 v[40:41], v[222:223]
	v_mov_b64_e32 v[72:73], v[236:237]
	v_mov_b64_e32 v[74:75], v[238:239]
	s_waitcnt vmcnt(0)
	v_pk_add_f32 v[8:9], v[74:75], 1.0 op_sel_hi:[1,0]
	v_pk_add_f32 v[72:73], v[72:73], 1.0 op_sel_hi:[1,0]
	v_pk_mul_f32 v[2:3], v[8:9], v[2:3]
	v_pk_mul_f32 v[4:5], v[72:73], v[4:5]
	v_pk_fma_f32 v[40:41], v[40:41], s[92:93], v[2:3] op_sel_hi:[1,0,1]
	v_pk_fma_f32 v[38:39], v[38:39], s[92:93], v[4:5] op_sel_hi:[1,0,1]
	v_mov_b64_e32 v[2:3], v[240:241]
	v_mov_b64_e32 v[4:5], v[242:243]
	s_nop 0
	v_mov_b64_e32 v[6:7], v[140:141]
	v_mov_b64_e32 v[8:9], v[142:143]
	s_waitcnt vmcnt(0)
	v_pk_add_f32 v[8:9], v[8:9], 1.0 op_sel_hi:[1,0]
	v_pk_add_f32 v[6:7], v[6:7], 1.0 op_sel_hi:[1,0]
	v_pk_mul_f32 v[8:9], v[68:69], v[8:9]
	v_pk_mul_f32 v[6:7], v[70:71], v[6:7]
	v_pk_fma_f32 v[4:5], v[4:5], s[92:93], v[8:9] op_sel_hi:[1,0,1]
	v_pk_fma_f32 v[2:3], v[2:3], s[92:93], v[6:7] op_sel_hi:[1,0,1]
	v_mov_b32_e32 v6, v66
	v_mov_b32_e32 v7, v62
	v_mov_b32_e32 v8, v67
	v_mov_b32_e32 v9, v63
	v_pk_add_f32 v[6:7], v[6:7], v[8:9]
	v_mov_b32_e32 v8, v64
	v_mov_b32_e32 v9, v60
	v_mov_b32_e32 v68, v65
	v_mov_b32_e32 v69, v61
	v_pk_add_f32 v[8:9], v[8:9], v[68:69]
	v_mov_b32_e32 v68, v56
	v_pk_add_f32 v[6:7], v[6:7], v[8:9]
	v_pk_mov_b32 v[8:9], v[56:57], v[58:59] op_sel:[1,0]
	v_mov_b32_e32 v69, v59
	v_pk_add_f32 v[8:9], v[8:9], v[68:69]
	v_add_f32_e32 v1, 0, v6
	v_pk_add_f32 v[8:9], v[8:9], v[8:9] op_sel:[0,1] op_sel_hi:[1,0]
	v_add_f32_e32 v6, v1, v7
	v_add_f32_e32 v68, v50, v51
	v_add_f32_e32 v70, v52, v53
	v_mov_b32_e32 v7, v46
	v_mov_b32_e32 v9, v47
	v_mov_b32_e32 v69, v48
	v_mov_b32_e32 v71, v49
	v_pk_add_f32 v[6:7], v[6:7], v[8:9]
	v_pk_add_f32 v[8:9], v[68:69], v[70:71]
	v_mov_b32_e32 v68, v42
	v_pk_add_f32 v[6:7], v[6:7], v[8:9]
	v_pk_mov_b32 v[8:9], v[42:43], v[44:45] op_sel:[1,0]
	v_mov_b32_e32 v69, v45
	v_pk_add_f32 v[8:9], v[8:9], v[68:69]
	v_pk_add_f32 v[6:7], v[6:7], v[6:7] op_sel:[0,1] op_sel_hi:[1,0]
	v_pk_add_f32 v[8:9], v[8:9], v[8:9] op_sel:[0,1] op_sel_hi:[1,0]
	v_add_f32_e32 v68, v38, v39
	v_add_f32_e32 v70, v40, v41
	v_mov_b32_e32 v7, v2
	v_mov_b32_e32 v9, v3
	v_mov_b32_e32 v69, v4
	v_mov_b32_e32 v71, v5
	v_pk_add_f32 v[6:7], v[6:7], v[8:9]
	v_pk_add_f32 v[8:9], v[68:69], v[70:71]
	s_nop 0
	v_pk_add_f32 v[6:7], v[6:7], v[8:9]
	s_nop 0
	v_add_f32_e32 v1, v6, v7
	v_and_b32_e32 v6, 64, v249
	v_add_u32_e32 v6, 64, v6
	v_xor_b32_e32 v7, 1, v249
	v_cmp_lt_i32_e32 vcc, v7, v6
	s_nop 1
	v_cndmask_b32_e32 v7, v249, v7, vcc
	v_lshlrev_b32_e32 v72, 2, v7
	ds_bpermute_b32 v7, v72, v1
	s_waitcnt lgkmcnt(0)
	v_add_f32_e32 v1, v1, v7
	v_xor_b32_e32 v7, 2, v249
	v_cmp_lt_i32_e32 vcc, v7, v6
	s_nop 1
	v_cndmask_b32_e32 v7, v249, v7, vcc
	v_lshlrev_b32_e32 v73, 2, v7
	ds_bpermute_b32 v7, v73, v1
	s_waitcnt lgkmcnt(0)
	v_add_f32_e32 v1, v1, v7
	v_xor_b32_e32 v7, 4, v249
	v_cmp_lt_i32_e32 vcc, v7, v6
	s_nop 1
	v_cndmask_b32_e32 v7, v249, v7, vcc
	v_lshlrev_b32_e32 v74, 2, v7
	ds_bpermute_b32 v7, v74, v1
	s_waitcnt lgkmcnt(0)
	v_add_f32_e32 v1, v1, v7
	v_xor_b32_e32 v7, 8, v249
	v_cmp_lt_i32_e32 vcc, v7, v6
	s_nop 1
	v_cndmask_b32_e32 v7, v249, v7, vcc
	v_lshlrev_b32_e32 v75, 2, v7
	ds_bpermute_b32 v7, v75, v1
	s_waitcnt lgkmcnt(0)
	v_add_f32_e32 v1, v1, v7
	v_xor_b32_e32 v7, 16, v249
	v_cmp_lt_i32_e32 vcc, v7, v6
	s_nop 1
	v_cndmask_b32_e32 v7, v249, v7, vcc
	v_lshlrev_b32_e32 v76, 2, v7
	ds_bpermute_b32 v7, v76, v1
	s_waitcnt lgkmcnt(0)
	v_add_f32_e32 v1, v1, v7
	v_xor_b32_e32 v7, 32, v249
	v_cmp_lt_i32_e32 vcc, v7, v6
	s_nop 1
	v_cndmask_b32_e32 v6, v249, v7, vcc
	v_lshlrev_b32_e32 v77, 2, v6
	ds_bpermute_b32 v6, v77, v1
	s_waitcnt lgkmcnt(0)
	v_add_f32_e32 v1, v1, v6
	v_fmamk_f32 v67, v1, 0xba000000, v67
	v_fmamk_f32 v63, v1, 0xba000000, v63
	v_fmamk_f32 v65, v1, 0xba000000, v65
	v_fmac_f32_e32 v66, 0xba000000, v1
	v_fmamk_f32 v61, v1, 0xba000000, v61
	v_fmac_f32_e32 v62, 0xba000000, v1
	v_mov_b32_e32 v8, v67
	v_mov_b32_e32 v9, v63
	v_fmac_f32_e32 v64, 0xba000000, v1
	v_fmac_f32_e32 v60, 0xba000000, v1
	v_mov_b32_e32 v6, v66
	v_mov_b32_e32 v7, v62
	v_pk_mul_f32 v[8:9], v[8:9], v[8:9]
	v_mov_b32_e32 v68, v65
	v_mov_b32_e32 v69, v61
	v_pk_fma_f32 v[6:7], v[6:7], v[6:7], v[8:9]
	v_mov_b32_e32 v8, v64
	v_mov_b32_e32 v9, v60
	v_pk_mul_f32 v[68:69], v[68:69], v[68:69]
	v_fmamk_f32 v57, v1, 0xba000000, v57
	v_pk_fma_f32 v[8:9], v[8:9], v[8:9], v[68:69]
	v_fmac_f32_e32 v56, 0xba000000, v1
	v_pk_add_f32 v[6:7], v[6:7], v[8:9]
	v_fmamk_f32 v59, v1, 0xba000000, v59
	v_fmac_f32_e32 v58, 0xba000000, v1
	v_pk_add_f32 v[6:7], v[6:7], v[6:7] op_sel_hi:[0,1]
	v_pk_mul_f32 v[8:9], v[58:59], v[58:59]
	v_pk_mul_f32 v[68:69], v[56:57], v[56:57]
	v_fmac_f32_e32 v50, 0xba000000, v1
	v_pk_mov_b32 v[70:71], v[68:69], v[8:9] op_sel:[1,0]
	v_mov_b32_e32 v69, v9
	v_fmamk_f32 v51, v1, 0xba000000, v51
	v_fmac_f32_e32 v52, 0xba000000, v1
	v_mul_f32_e32 v6, v50, v50
	v_pk_add_f32 v[8:9], v[70:71], v[68:69]
	v_fmamk_f32 v53, v1, 0xba000000, v53
	v_pk_fma_f32 v[68:69], v[50:51], v[50:51], v[6:7] op_sel_hi:[1,1,0]
	v_mul_f32_e32 v6, v52, v52
	v_pk_add_f32 v[8:9], v[8:9], v[8:9] op_sel_hi:[0,1]
	v_pk_fma_f32 v[70:71], v[52:53], v[52:53], v[6:7] op_sel_hi:[1,1,0]
	v_fmamk_f32 v49, v1, 0xba000000, v49
	v_fmac_f32_e32 v48, 0xba000000, v1
	v_fmamk_f32 v47, v1, 0xba000000, v47
	v_fmac_f32_e32 v46, 0xba000000, v1
	v_mul_f32_e32 v68, v46, v46
	v_mul_f32_e32 v70, v47, v47
	v_mul_f32_e32 v8, v48, v48
	v_mul_f32_e32 v6, v49, v49
	v_pk_add_f32 v[68:69], v[68:69], v[70:71]
	v_pk_add_f32 v[6:7], v[8:9], v[6:7]
	v_fmamk_f32 v43, v1, 0xba000000, v43
	v_pk_add_f32 v[6:7], v[68:69], v[6:7]
	v_fmac_f32_e32 v42, 0xba000000, v1
	v_fmamk_f32 v45, v1, 0xba000000, v45
	v_fmac_f32_e32 v44, 0xba000000, v1
	v_pk_add_f32 v[6:7], v[6:7], v[6:7] op_sel_hi:[0,1]
	v_pk_mul_f32 v[8:9], v[44:45], v[44:45]
	v_pk_mul_f32 v[68:69], v[42:43], v[42:43]
	v_fmac_f32_e32 v38, 0xba000000, v1
	v_pk_mov_b32 v[70:71], v[68:69], v[8:9] op_sel:[1,0]
	v_mov_b32_e32 v69, v9
	v_fmamk_f32 v39, v1, 0xba000000, v39
	v_fmac_f32_e32 v40, 0xba000000, v1
	v_mul_f32_e32 v6, v38, v38
	v_pk_add_f32 v[8:9], v[70:71], v[68:69]
	v_fmamk_f32 v41, v1, 0xba000000, v41
	v_pk_fma_f32 v[68:69], v[38:39], v[38:39], v[6:7] op_sel_hi:[1,1,0]
	v_mul_f32_e32 v6, v40, v40
	v_pk_add_f32 v[8:9], v[8:9], v[8:9] op_sel_hi:[0,1]
	v_pk_fma_f32 v[70:71], v[40:41], v[40:41], v[6:7] op_sel_hi:[1,1,0]
	v_fmamk_f32 v5, v1, 0xba000000, v5
	v_fmac_f32_e32 v4, 0xba000000, v1
	v_fmamk_f32 v3, v1, 0xba000000, v3
	v_fmac_f32_e32 v2, 0xba000000, v1
	v_mul_f32_e32 v68, v2, v2
	v_mul_f32_e32 v70, v3, v3
	v_mul_f32_e32 v8, v4, v4
	v_mul_f32_e32 v6, v5, v5
	v_pk_add_f32 v[68:69], v[68:69], v[70:71]
	v_pk_add_f32 v[6:7], v[8:9], v[6:7]
	s_nop 0
	v_pk_add_f32 v[6:7], v[68:69], v[6:7]
	s_nop 0
	v_add_f32_e32 v1, v6, v7
	ds_bpermute_b32 v6, v72, v1
	s_waitcnt lgkmcnt(0)
	v_add_f32_e32 v1, v1, v6
	ds_bpermute_b32 v6, v73, v1
	s_waitcnt lgkmcnt(0)
	v_add_f32_e32 v1, v1, v6
	ds_bpermute_b32 v6, v74, v1
	s_waitcnt lgkmcnt(0)
	v_add_f32_e32 v1, v1, v6
	ds_bpermute_b32 v6, v75, v1
	s_waitcnt lgkmcnt(0)
	v_add_f32_e32 v1, v1, v6
	ds_bpermute_b32 v6, v76, v1
	s_waitcnt lgkmcnt(0)
	v_add_f32_e32 v1, v1, v6
	ds_bpermute_b32 v6, v77, v1
	s_waitcnt lgkmcnt(0)
	v_add_f32_e32 v1, v1, v6
	v_fmamk_f32 v1, v1, 0x3a000000, v250
	v_cmp_gt_f32_e32 vcc, s96, v1
	v_mul_f32_e32 v6, 0x4f800000, v1
	s_nop 0
	v_cndmask_b32_e32 v1, v1, v6, vcc
	v_sqrt_f32_e32 v6, v1
	s_nop 0
	v_add_u32_e32 v7, -1, v6
	v_fma_f32 v8, -v7, v6, v1
	v_cmp_ge_f32_e64 s[10:11], 0, v8
	v_add_u32_e32 v8, 1, v6
	s_nop 0
	v_cndmask_b32_e64 v7, v6, v7, s[10:11]
	v_fma_f32 v6, -v8, v6, v1
	v_cmp_lt_f32_e64 s[10:11], 0, v6
	s_nop 1
	v_cndmask_b32_e64 v6, v7, v8, s[10:11]
	v_mul_f32_e32 v7, 0x37800000, v6
	v_cndmask_b32_e32 v6, v6, v7, vcc
	v_cmp_class_f32_e32 vcc, v1, v251
	s_nop 1
	v_cndmask_b32_e32 v1, v6, v1, vcc
	v_div_scale_f32 v6, s[10:11], v1, v1, 1.0
	v_rcp_f32_e32 v7, v6
	s_lshl_b64 s[10:11], s[16:17], 13
	v_fma_f32 v8, -v6, v7, 1.0
	v_fmac_f32_e32 v7, v8, v7
	v_div_scale_f32 v8, vcc, 1.0, v1, 1.0
	v_mul_f32_e32 v9, v8, v7
	v_fma_f32 v68, -v6, v9, v8
	v_fmac_f32_e32 v9, v68, v7
	global_load_dwordx4 v[68:71], v[14:15], off
	global_load_dwordx4 v[72:75], v[16:17], off
	v_fma_f32 v6, -v6, v9, v8
	v_div_fmas_f32 v6, v6, v7, v9
	v_div_fixup_f32 v6, v6, v1, 1.0
	v_pk_mul_f32 v[64:65], v[64:65], v[6:7] op_sel_hi:[1,0]
	v_pk_mul_f32 v[8:9], v[66:67], v[6:7] op_sel_hi:[1,0]
	v_lshl_add_u64 v[66:67], v[34:35], 0, s[10:11]
	s_mov_b64 s[10:11], 0x8000
	v_lshl_add_u64 v[80:81], v[54:55], 0, s[10:11]
	s_mov_b64 s[10:11], 0x6000
	v_lshl_add_u64 v[84:85], v[54:55], 0, s[10:11]
	s_lshl_b64 s[10:11], s[16:17], 12
	s_waitcnt vmcnt(0)
	v_pk_fma_f32 v[70:71], v[70:71], v[64:65], v[74:75]
	v_add_co_u32_e32 v64, vcc, s9, v54
	v_pk_fma_f32 v[68:69], v[68:69], v[8:9], v[72:73]
	s_nop 0
	v_addc_co_u32_e32 v65, vcc, 0, v55, vcc
	s_movk_i32 s9, 0x7000
	global_store_dwordx4 v[66:67], v[68:71], off
	v_add_co_u32_e32 v54, vcc, s9, v54
	global_load_dwordx4 v[72:75], v[64:65], off offset:-4096
	s_nop 0
	v_addc_co_u32_e32 v55, vcc, 0, v55, vcc
	global_load_dwordx4 v[76:79], v[54:55], off offset:-4096
	s_waitcnt vmcnt(1)
	v_pk_add_f32 v[72:73], v[72:73], 1.0 op_sel_hi:[1,0]
	v_pk_add_f32 v[8:9], v[74:75], 1.0 op_sel_hi:[1,0]
	s_waitcnt vmcnt(0)
	v_pk_fma_f32 v[68:69], v[72:73], v[68:69], v[76:77]
	s_nop 0
	s_nop 0
	s_nop 0
	s_nop 0
	v_pk_fma_f32 v[8:9], v[8:9], v[70:71], v[78:79]
	s_nop 0
	s_nop 0
	v_cvt_pk_bf16_f32 v68, v68, v69
	v_bfe_u32 v1, v8, 16, 1
	v_add3_u32 v1, v8, v1, s73
	v_bfe_u32 v7, v9, 16, 1
	v_lshrrev_b32_e32 v1, 16, v1
	v_add3_u32 v7, v9, v7, s73
	v_and_or_b32 v69, v7, s33, v1
	v_lshl_add_u64 v[8:9], v[36:37], 0, s[10:11]
	global_store_dwordx2 v[8:9], v[68:69], off
	global_load_dwordx4 v[68:71], v[14:15], off offset:1024
	s_nop 0
	global_load_dwordx4 v[72:75], v[16:17], off offset:1024
	v_pk_mul_f32 v[76:77], v[60:61], v[6:7] op_sel_hi:[1,0]
	v_pk_mul_f32 v[60:61], v[62:63], v[6:7] op_sel_hi:[1,0]
	s_waitcnt vmcnt(0)
	v_pk_fma_f32 v[62:63], v[70:71], v[76:77], v[74:75]
	v_pk_fma_f32 v[60:61], v[68:69], v[60:61], v[72:73]
	global_store_dwordx4 v[66:67], v[60:63], off offset:1024
	global_load_dwordx4 v[68:71], v[80:81], off offset:1024
	global_load_dwordx4 v[72:75], v[84:85], off offset:1024
	s_waitcnt vmcnt(1)
	v_pk_add_f32 v[68:69], v[68:69], 1.0 op_sel_hi:[1,0]
	s_waitcnt vmcnt(0)
	v_pk_fma_f32 v[60:61], v[68:69], v[60:61], v[72:73]
	v_pk_add_f32 v[70:71], v[70:71], 1.0 op_sel_hi:[1,0]
	v_pk_fma_f32 v[62:63], v[70:71], v[62:63], v[74:75]
	v_cvt_pk_bf16_f32 v60, v60, v61
	v_bfe_u32 v1, v62, 16, 1
	v_add3_u32 v1, v62, v1, s73
	v_bfe_u32 v7, v63, 16, 1
	v_lshrrev_b32_e32 v1, 16, v1
	v_add3_u32 v7, v63, v7, s73
	v_and_or_b32 v61, v7, s33, v1
	global_store_dwordx2 v[8:9], v[60:61], off offset:512
	global_load_dwordx4 v[60:63], v[14:15], off offset:2048
	s_nop 0
	global_load_dwordx4 v[68:71], v[16:17], off offset:2048
	v_pk_mul_f32 v[58:59], v[58:59], v[6:7] op_sel_hi:[1,0]
	v_pk_mul_f32 v[56:57], v[56:57], v[6:7] op_sel_hi:[1,0]
	s_waitcnt vmcnt(0)
	v_pk_fma_f32 v[58:59], v[62:63], v[58:59], v[70:71]
	v_pk_fma_f32 v[56:57], v[60:61], v[56:57], v[68:69]
	global_store_dwordx4 v[66:67], v[56:59], off offset:2048
	global_load_dwordx4 v[60:63], v[80:81], off offset:2048
	global_load_dwordx4 v[68:71], v[84:85], off offset:2048
	s_waitcnt vmcnt(1)
	v_pk_add_f32 v[60:61], v[60:61], 1.0 op_sel_hi:[1,0]
	s_waitcnt vmcnt(0)
	v_pk_fma_f32 v[56:57], v[56:57], v[60:61], v[68:69]
	v_pk_add_f32 v[62:63], v[62:63], 1.0 op_sel_hi:[1,0]
	v_pk_fma_f32 v[58:59], v[58:59], v[62:63], v[70:71]
	v_cvt_pk_bf16_f32 v56, v56, v57
	v_bfe_u32 v1, v58, 16, 1
	v_add3_u32 v1, v58, v1, s73
	v_bfe_u32 v7, v59, 16, 1
	v_lshrrev_b32_e32 v1, 16, v1
	v_add3_u32 v7, v59, v7, s73
	v_and_or_b32 v57, v7, s33, v1
	global_store_dwordx2 v[8:9], v[56:57], off offset:1024
	global_load_dwordx4 v[56:59], v[14:15], off offset:3072
	s_nop 0
	global_load_dwordx4 v[60:63], v[16:17], off offset:3072
	v_pk_mul_f32 v[52:53], v[52:53], v[6:7] op_sel_hi:[1,0]
	v_pk_mul_f32 v[50:51], v[50:51], v[6:7] op_sel_hi:[1,0]
	s_waitcnt vmcnt(0)
	v_pk_fma_f32 v[52:53], v[52:53], v[58:59], v[62:63]
	v_pk_fma_f32 v[50:51], v[50:51], v[56:57], v[60:61]
	global_store_dwordx4 v[66:67], v[50:53], off offset:3072
	global_load_dwordx4 v[56:59], v[80:81], off offset:3072
	global_load_dwordx4 v[60:63], v[84:85], off offset:3072
	s_waitcnt vmcnt(1)
	v_pk_add_f32 v[56:57], v[56:57], 1.0 op_sel_hi:[1,0]
	s_waitcnt vmcnt(0)
	v_pk_fma_f32 v[50:51], v[50:51], v[56:57], v[60:61]
	v_pk_add_f32 v[58:59], v[58:59], 1.0 op_sel_hi:[1,0]
	v_pk_fma_f32 v[52:53], v[52:53], v[58:59], v[62:63]
	v_cvt_pk_bf16_f32 v50, v50, v51
	v_bfe_u32 v1, v52, 16, 1
	v_add3_u32 v1, v52, v1, s73
	v_bfe_u32 v7, v53, 16, 1
	v_lshrrev_b32_e32 v1, 16, v1
	v_add3_u32 v7, v53, v7, s73
	v_and_or_b32 v51, v7, s33, v1
	global_store_dwordx2 v[8:9], v[50:51], off offset:1536
	global_load_dwordx4 v[50:53], v[18:19], off
	s_nop 0
	global_load_dwordx4 v[56:59], v[20:21], off
	v_pk_mul_f32 v[46:47], v[46:47], v[6:7] op_sel_hi:[1,0]
	v_pk_mul_f32 v[60:61], v[48:49], v[6:7] op_sel_hi:[1,0]
	s_waitcnt vmcnt(0)
	v_pk_fma_f32 v[48:49], v[46:47], v[50:51], v[56:57]
	v_add_co_u32_e32 v46, vcc, s82, v66
	v_pk_fma_f32 v[50:51], v[60:61], v[52:53], v[58:59]
	s_nop 0
	v_addc_co_u32_e32 v47, vcc, 0, v67, vcc
	global_store_dwordx4 v[46:47], v[48:51], off
	global_load_dwordx4 v[56:59], v[64:65], off
	global_load_dwordx4 v[60:63], v[54:55], off
	s_waitcnt vmcnt(1)
	v_pk_add_f32 v[56:57], v[56:57], 1.0 op_sel_hi:[1,0]
	s_waitcnt vmcnt(0)
	v_pk_fma_f32 v[48:49], v[48:49], v[56:57], v[60:61]
	v_pk_add_f32 v[52:53], v[58:59], 1.0 op_sel_hi:[1,0]
	v_pk_fma_f32 v[50:51], v[50:51], v[52:53], v[62:63]
	v_cvt_pk_bf16_f32 v48, v48, v49
	v_bfe_u32 v1, v50, 16, 1
	v_add3_u32 v1, v50, v1, s73
	v_bfe_u32 v7, v51, 16, 1
	v_lshrrev_b32_e32 v1, 16, v1
	v_add3_u32 v7, v51, v7, s73
	v_and_or_b32 v49, v7, s33, v1
	global_store_dwordx2 v[8:9], v[48:49], off offset:2048
	global_load_dwordx4 v[48:51], v[22:23], off
	s_nop 0
	global_load_dwordx4 v[56:59], v[24:25], off
	v_pk_mul_f32 v[44:45], v[44:45], v[6:7] op_sel_hi:[1,0]
	v_pk_mul_f32 v[42:43], v[42:43], v[6:7] op_sel_hi:[1,0]
	s_waitcnt vmcnt(0)
	v_pk_fma_f32 v[44:45], v[44:45], v[50:51], v[58:59]
	v_pk_fma_f32 v[42:43], v[42:43], v[48:49], v[56:57]
	global_store_dwordx4 v[46:47], v[42:45], off offset:1024
	global_load_dwordx4 v[48:51], v[64:65], off offset:1024
	global_load_dwordx4 v[56:59], v[54:55], off offset:1024
	s_waitcnt vmcnt(1)
	v_pk_add_f32 v[48:49], v[48:49], 1.0 op_sel_hi:[1,0]
	s_waitcnt vmcnt(0)
	v_pk_fma_f32 v[42:43], v[42:43], v[48:49], v[56:57]
	v_pk_add_f32 v[50:51], v[50:51], 1.0 op_sel_hi:[1,0]
	v_pk_fma_f32 v[44:45], v[44:45], v[50:51], v[58:59]
	v_cvt_pk_bf16_f32 v42, v42, v43
	v_bfe_u32 v1, v44, 16, 1
	v_add3_u32 v1, v44, v1, s73
	v_bfe_u32 v7, v45, 16, 1
	v_lshrrev_b32_e32 v1, 16, v1
	v_add3_u32 v7, v45, v7, s73
	v_and_or_b32 v43, v7, s33, v1
	global_store_dwordx2 v[8:9], v[42:43], off offset:2560
	global_load_dwordx4 v[42:45], v[26:27], off
	s_nop 0
	global_load_dwordx4 v[48:51], v[28:29], off
	v_pk_mul_f32 v[40:41], v[40:41], v[6:7] op_sel_hi:[1,0]
	v_pk_mul_f32 v[38:39], v[38:39], v[6:7] op_sel_hi:[1,0]
	s_waitcnt vmcnt(0)
	v_pk_fma_f32 v[40:41], v[40:41], v[44:45], v[50:51]
	v_pk_fma_f32 v[38:39], v[38:39], v[42:43], v[48:49]
	global_store_dwordx4 v[46:47], v[38:41], off offset:2048
	global_load_dwordx4 v[42:45], v[64:65], off offset:2048
	global_load_dwordx4 v[48:51], v[54:55], off offset:2048
	s_waitcnt vmcnt(1)
	v_pk_add_f32 v[42:43], v[42:43], 1.0 op_sel_hi:[1,0]
	s_waitcnt vmcnt(0)
	v_pk_fma_f32 v[38:39], v[38:39], v[42:43], v[48:49]
	v_pk_add_f32 v[44:45], v[44:45], 1.0 op_sel_hi:[1,0]
	v_pk_fma_f32 v[40:41], v[40:41], v[44:45], v[50:51]
	v_cvt_pk_bf16_f32 v38, v38, v39
	v_bfe_u32 v1, v40, 16, 1
	v_add3_u32 v1, v40, v1, s73
	v_bfe_u32 v7, v41, 16, 1
	v_lshrrev_b32_e32 v1, 16, v1
	v_add3_u32 v7, v41, v7, s73
	v_and_or_b32 v39, v7, s33, v1
	global_store_dwordx2 v[8:9], v[38:39], off offset:3072
	global_load_dwordx4 v[38:41], v[30:31], off
	s_nop 0
	global_load_dwordx4 v[42:45], v[32:33], off
	v_pk_mul_f32 v[4:5], v[4:5], v[6:7] op_sel_hi:[1,0]
	v_pk_mul_f32 v[2:3], v[2:3], v[6:7] op_sel_hi:[1,0]
	s_waitcnt vmcnt(0)
	v_pk_fma_f32 v[4:5], v[4:5], v[40:41], v[44:45]
	v_pk_fma_f32 v[2:3], v[2:3], v[38:39], v[42:43]
	global_store_dwordx4 v[46:47], v[2:5], off offset:3072
	global_load_dwordx4 v[38:41], v[64:65], off offset:3072
	global_load_dwordx4 v[42:45], v[54:55], off offset:3072
	s_waitcnt vmcnt(1)
	v_pk_add_f32 v[38:39], v[38:39], 1.0 op_sel_hi:[1,0]
	s_waitcnt vmcnt(0)
	v_pk_fma_f32 v[2:3], v[2:3], v[38:39], v[42:43]
	v_pk_add_f32 v[6:7], v[40:41], 1.0 op_sel_hi:[1,0]
	v_pk_fma_f32 v[4:5], v[4:5], v[6:7], v[44:45]
	v_cvt_pk_bf16_f32 v2, v2, v3
	v_bfe_u32 v1, v4, 16, 1
	v_add3_u32 v1, v4, v1, s73
	v_bfe_u32 v3, v5, 16, 1
	v_lshrrev_b32_e32 v1, 16, v1
	v_add3_u32 v3, v5, v3, s73
	v_and_or_b32 v3, v3, s33, v1
	global_store_dwordx2 v[8:9], v[2:3], off offset:3584
	s_branch .LBB0_1221
